# E27: P6 EpiRes: all 16 bf16 residual loads of a unit issued together at the epilogue top into unused VGPRs (no load waits behind the previous batch's stores); counted waits re-derived
# baseline (speedup 1.0000x reference)
.LBB0_1037:
	s_andn2_b64 vcc, exec, s[40:41]
	v_mbcnt_lo_u32_b32 v138, -1, 0
	v_mbcnt_hi_u32_b32 v138, -1, v138
	s_cbranch_vccnz .LBB0_1039
	v_and_or_b32 v139, v138, 15, s53
	s_lshl_b32 s44, s61, 8
	v_ashrrev_i32_e32 v138, 1, v138
	v_lshl_add_u32 v140, s60, 8, v139
	s_or_b32 s44, s44, s54
	v_and_b32_e32 v138, -8, v138
	v_ashrrev_i32_e32 v141, 31, v140
	v_add_u32_e32 v138, s44, v138
	v_readlane_b32 s12, v250, 2
	v_ashrrev_i32_e32 v139, 31, v138
	v_lshlrev_b64 v[142:143], 13, v[140:141]
	v_readlane_b32 s13, v250, 3
	v_or_b32_e32 v146, 16, v140
	v_lshlrev_b64 v[138:139], 1, v[138:139]
	v_lshl_add_u64 v[142:143], s[12:13], 0, v[142:143]
	v_ashrrev_i32_e32 v147, 31, v146
	v_lshl_add_u64 v[144:145], v[142:143], 0, v[138:139]
	v_lshl_add_u64 v[142:143], s[12:13], 0, v[138:139]
	v_lshlrev_b64 v[146:147], 13, v[146:147]
	v_lshl_add_u64 v[146:147], v[142:143], 0, v[146:147]
	global_load_dwordx4 v[154:157], v[144:145], off
	global_load_dwordx4 v[158:161], v[146:147], off
	v_or_b32_e32 v146, 32, v140
	v_ashrrev_i32_e32 v147, 31, v146
	v_lshlrev_b64 v[146:147], 13, v[146:147]
	v_lshl_add_u64 v[146:147], v[142:143], 0, v[146:147]
	global_load_dwordx4 v[162:165], v[146:147], off
	v_or_b32_e32 v146, 48, v140
	v_ashrrev_i32_e32 v147, 31, v146
	v_lshlrev_b64 v[146:147], 13, v[146:147]
	v_lshl_add_u64 v[146:147], v[142:143], 0, v[146:147]
	global_load_dwordx4 v[166:169], v[146:147], off
	s_mov_b32 s99, 0
	global_load_dwordx4 v[178:181], v[144:145], off offset:256
	s_mov_b32 s98, 0x20000
	v_lshl_add_u64 v[242:243], v[144:145], 0, s[98:99]
	global_load_dwordx4 v[182:185], v[242:243], off offset:256
	s_mov_b32 s98, 0x40000
	v_lshl_add_u64 v[244:245], v[144:145], 0, s[98:99]
	global_load_dwordx4 v[186:189], v[244:245], off offset:256
	s_mov_b32 s98, 0x60000
	v_lshl_add_u64 v[246:247], v[144:145], 0, s[98:99]
	global_load_dwordx4 v[190:193], v[246:247], off offset:256
	s_mov_b32 s98, 0x100000
	v_lshl_add_u64 v[242:243], v[144:145], 0, s[98:99]
	global_load_dwordx4 v[194:197], v[242:243], off
	s_mov_b32 s98, 0x120000
	v_lshl_add_u64 v[244:245], v[144:145], 0, s[98:99]
	global_load_dwordx4 v[198:201], v[244:245], off
	s_mov_b32 s98, 0x140000
	v_lshl_add_u64 v[246:247], v[144:145], 0, s[98:99]
	global_load_dwordx4 v[202:205], v[246:247], off
	s_mov_b32 s98, 0x160000
	v_lshl_add_u64 v[248:249], v[144:145], 0, s[98:99]
	global_load_dwordx4 v[206:209], v[248:249], off
	global_load_dwordx4 v[210:213], v[242:243], off offset:256
	global_load_dwordx4 v[214:217], v[244:245], off offset:256
	global_load_dwordx4 v[218:221], v[246:247], off offset:256
	global_load_dwordx4 v[222:225], v[248:249], off offset:256
	v_add_u32_e32 v146, 16, v140
	v_add_u32_e32 v148, 32, v140
	v_ashrrev_i32_e32 v147, 31, v146
	v_ashrrev_i32_e32 v149, 31, v148
	v_lshlrev_b64 v[146:147], 13, v[146:147]
	v_lshlrev_b64 v[148:149], 13, v[148:149]
	v_lshl_add_u64 v[146:147], s[12:13], 0, v[146:147]
	v_lshl_add_u64 v[170:171], s[12:13], 0, v[148:149]
	v_lshl_add_u64 v[148:149], v[146:147], 0, v[138:139]
	v_lshl_add_u64 v[146:147], v[170:171], 0, v[138:139]
	s_waitcnt vmcnt(12)
	v_lshlrev_b32_e32 v170, 16, v154
	v_and_b32_e32 v171, 0xffff0000, v154
	v_lshlrev_b32_e32 v154, 16, v155
	v_and_b32_e32 v155, 0xffff0000, v155
	v_lshlrev_b32_e32 v172, 16, v156
	v_and_b32_e32 v173, 0xffff0000, v156
	v_lshlrev_b32_e32 v156, 16, v157
	v_and_b32_e32 v157, 0xffff0000, v157
	v_pk_add_f32 v[126:127], v[126:127], v[154:155]
	v_pk_add_f32 v[124:125], v[124:125], v[170:171]
	v_pk_add_f32 v[154:155], v[122:123], v[156:157]
	v_pk_add_f32 v[122:123], v[120:121], v[172:173]
	v_lshlrev_b32_e32 v156, 16, v158
	v_and_b32_e32 v157, 0xffff0000, v158
	v_lshlrev_b32_e32 v158, 16, v159
	v_and_b32_e32 v159, 0xffff0000, v159
	v_lshlrev_b32_e32 v170, 16, v160
	v_and_b32_e32 v171, 0xffff0000, v160
	v_lshlrev_b32_e32 v160, 16, v161
	v_and_b32_e32 v161, 0xffff0000, v161
	v_lshlrev_b32_e32 v174, 16, v164
	v_and_b32_e32 v175, 0xffff0000, v164
	v_lshlrev_b32_e32 v164, 16, v165
	v_and_b32_e32 v165, 0xffff0000, v165
	v_lshlrev_b32_e32 v172, 16, v162
	v_and_b32_e32 v173, 0xffff0000, v162
	v_lshlrev_b32_e32 v162, 16, v163
	v_and_b32_e32 v163, 0xffff0000, v163
	v_cvt_pk_bf16_f32 v120, v124, v125
	v_cvt_pk_bf16_f32 v121, v126, v127
	v_cvt_pk_bf16_f32 v122, v122, v123
	v_cvt_pk_bf16_f32 v123, v154, v155
	v_pk_add_f32 v[118:119], v[118:119], v[158:159]
	v_pk_add_f32 v[116:117], v[116:117], v[156:157]
	v_pk_add_f32 v[114:115], v[114:115], v[160:161]
	v_pk_add_f32 v[112:113], v[112:113], v[170:171]
	v_pk_add_f32 v[124:125], v[106:107], v[164:165]
	v_pk_add_f32 v[126:127], v[104:105], v[174:175]
	global_store_dwordx4 v[144:145], v[120:123], off
	v_cvt_pk_bf16_f32 v104, v116, v117
	v_cvt_pk_bf16_f32 v105, v118, v119
	v_cvt_pk_bf16_f32 v106, v112, v113
	v_cvt_pk_bf16_f32 v107, v114, v115
	v_pk_add_f32 v[110:111], v[110:111], v[162:163]
	v_pk_add_f32 v[108:109], v[108:109], v[172:173]
	global_store_dwordx4 v[148:149], v[104:107], off
	v_lshlrev_b32_e32 v176, 16, v166
	v_and_b32_e32 v177, 0xffff0000, v166
	v_cvt_pk_bf16_f32 v104, v108, v109
	v_cvt_pk_bf16_f32 v105, v110, v111
	v_cvt_pk_bf16_f32 v106, v126, v127
	v_cvt_pk_bf16_f32 v107, v124, v125
	global_store_dwordx4 v[146:147], v[104:107], off
	v_lshlrev_b32_e32 v108, 16, v169
	v_and_b32_e32 v109, 0xffff0000, v169
	v_lshlrev_b32_e32 v106, 16, v168
	v_and_b32_e32 v107, 0xffff0000, v168
	v_lshlrev_b32_e32 v104, 16, v167
	v_and_b32_e32 v105, 0xffff0000, v167
	v_pk_add_f32 v[100:101], v[100:101], v[176:177]
	v_pk_add_f32 v[96:97], v[96:97], v[106:107]
	v_pk_add_f32 v[102:103], v[102:103], v[104:105]
	v_pk_add_f32 v[104:105], v[98:99], v[108:109]
	v_cvt_pk_bf16_f32 v98, v100, v101
	v_cvt_pk_bf16_f32 v99, v102, v103
	v_cvt_pk_bf16_f32 v100, v96, v97
	v_add_u32_e32 v96, 48, v140
	v_ashrrev_i32_e32 v97, 31, v96
	v_lshlrev_b64 v[96:97], 13, v[96:97]
	v_lshl_add_u64 v[96:97], s[12:13], 0, v[96:97]
	v_lshl_add_u64 v[96:97], v[96:97], 0, v[138:139]
	v_cvt_pk_bf16_f32 v101, v104, v105
	s_waitcnt vmcnt(11)
	v_lshlrev_b32_e32 v118, 16, v182
	global_store_dwordx4 v[96:97], v[98:101], off
	s_waitcnt vmcnt(12)
	v_lshlrev_b32_e32 v124, 16, v188
	v_and_b32_e32 v125, 0xffff0000, v188
	v_lshlrev_b32_e32 v98, 16, v178
	v_and_b32_e32 v99, 0xffff0000, v178
	v_lshlrev_b32_e32 v100, 16, v179
	v_and_b32_e32 v101, 0xffff0000, v179
	v_lshlrev_b32_e32 v102, 16, v180
	v_and_b32_e32 v103, 0xffff0000, v180
	s_waitcnt vmcnt(12)
	v_lshlrev_b32_e32 v126, 16, v190
	v_and_b32_e32 v127, 0xffff0000, v190
	v_lshlrev_b32_e32 v114, 16, v191
	v_and_b32_e32 v115, 0xffff0000, v191
	v_lshlrev_b32_e32 v104, 16, v181
	v_and_b32_e32 v105, 0xffff0000, v181
	v_and_b32_e32 v119, 0xffff0000, v182
	v_lshlrev_b32_e32 v106, 16, v183
	v_and_b32_e32 v107, 0xffff0000, v183
	v_lshlrev_b32_e32 v120, 16, v184
	v_and_b32_e32 v121, 0xffff0000, v184
	v_pk_add_f32 v[94:95], v[94:95], v[100:101]
	v_pk_add_f32 v[92:93], v[92:93], v[98:99]
	v_pk_add_f32 v[88:89], v[88:89], v[102:103]
	v_pk_add_f32 v[98:99], v[72:73], v[124:125]
	v_pk_add_f32 v[100:101], v[70:71], v[114:115]
	v_cvt_pk_bf16_f32 v70, v92, v93
	v_cvt_pk_bf16_f32 v71, v94, v95
	v_cvt_pk_bf16_f32 v72, v88, v89
	v_lshlrev_b32_e32 v108, 16, v185
	v_and_b32_e32 v109, 0xffff0000, v185
	v_lshlrev_b32_e32 v122, 16, v186
	v_and_b32_e32 v123, 0xffff0000, v186
	v_lshlrev_b32_e32 v110, 16, v187
	v_and_b32_e32 v111, 0xffff0000, v187
	v_lshlrev_b32_e32 v154, 16, v192
	v_and_b32_e32 v155, 0xffff0000, v192
	v_pk_add_f32 v[90:91], v[90:91], v[104:105]
	v_pk_add_f32 v[86:87], v[86:87], v[106:107]
	v_pk_add_f32 v[84:85], v[84:85], v[118:119]
	v_pk_add_f32 v[80:81], v[80:81], v[120:121]
	v_cvt_pk_bf16_f32 v73, v90, v91
	global_store_dwordx4 v[144:145], v[70:73], off offset:256
	v_lshlrev_b32_e32 v112, 16, v189
	v_and_b32_e32 v113, 0xffff0000, v189
	v_cvt_pk_bf16_f32 v70, v84, v85
	v_cvt_pk_bf16_f32 v71, v86, v87
	v_cvt_pk_bf16_f32 v72, v80, v81
	v_lshlrev_b32_e32 v116, 16, v193
	v_and_b32_e32 v117, 0xffff0000, v193
	v_pk_add_f32 v[82:83], v[82:83], v[108:109]
	v_pk_add_f32 v[78:79], v[78:79], v[110:111]
	v_pk_add_f32 v[76:77], v[76:77], v[122:123]
	v_cvt_pk_bf16_f32 v73, v82, v83
	global_store_dwordx4 v[148:149], v[70:73], off offset:256
	v_pk_add_f32 v[64:65], v[64:65], v[154:155]
	v_pk_add_f32 v[74:75], v[74:75], v[112:113]
	v_cvt_pk_bf16_f32 v70, v76, v77
	v_cvt_pk_bf16_f32 v71, v78, v79
	v_cvt_pk_bf16_f32 v72, v98, v99
	v_pk_add_f32 v[68:69], v[68:69], v[126:127]
	v_cvt_pk_bf16_f32 v73, v74, v75
	global_store_dwordx4 v[146:147], v[70:73], off offset:256
	v_pk_add_f32 v[66:67], v[66:67], v[116:117]
	v_add_u32_e32 v86, 0xb0, v140
	v_cvt_pk_bf16_f32 v70, v68, v69
	v_cvt_pk_bf16_f32 v71, v100, v101
	v_cvt_pk_bf16_f32 v72, v64, v65
	v_add_u32_e32 v64, 0x80, v140
	v_cvt_pk_bf16_f32 v73, v66, v67
	v_ashrrev_i32_e32 v65, 31, v64
	v_add_u32_e32 v66, 0x90, v140
	v_lshlrev_b64 v[64:65], 13, v[64:65]
	v_ashrrev_i32_e32 v67, 31, v66
	v_lshl_add_u64 v[64:65], s[12:13], 0, v[64:65]
	v_lshlrev_b64 v[66:67], 13, v[66:67]
	v_lshl_add_u64 v[64:65], v[64:65], 0, v[138:139]
	v_lshl_add_u64 v[68:69], v[142:143], 0, v[66:67]
	v_add_u32_e32 v68, 0xa0, v140
	v_ashrrev_i32_e32 v69, 31, v68
	v_lshlrev_b64 v[68:69], 13, v[68:69]
	v_lshl_add_u64 v[82:83], v[142:143], 0, v[68:69]
	v_ashrrev_i32_e32 v87, 31, v86
	v_lshlrev_b64 v[90:91], 13, v[86:87]
	v_lshl_add_u64 v[86:87], v[142:143], 0, v[90:91]
	v_lshl_add_u64 v[66:67], s[12:13], 0, v[66:67]
	v_lshl_add_u64 v[92:93], s[12:13], 0, v[68:69]
	global_store_dwordx4 v[96:97], v[70:73], off offset:256
	v_lshl_add_u64 v[68:69], v[66:67], 0, v[138:139]
	v_lshl_add_u64 v[66:67], v[92:93], 0, v[138:139]
	s_waitcnt vmcnt(12)
	v_lshlrev_b32_e32 v70, 16, v194
	v_and_b32_e32 v71, 0xffff0000, v194
	v_lshlrev_b32_e32 v72, 16, v195
	v_and_b32_e32 v73, 0xffff0000, v195
	v_lshlrev_b32_e32 v74, 16, v196
	v_and_b32_e32 v75, 0xffff0000, v196
	v_lshlrev_b32_e32 v76, 16, v197
	v_and_b32_e32 v77, 0xffff0000, v197
	s_waitcnt vmcnt(12)
	v_lshlrev_b32_e32 v98, 16, v204
	v_and_b32_e32 v99, 0xffff0000, v204
	v_lshlrev_b32_e32 v84, 16, v205
	v_and_b32_e32 v85, 0xffff0000, v205
	v_lshlrev_b32_e32 v92, 16, v198
	v_and_b32_e32 v93, 0xffff0000, v198
	v_lshlrev_b32_e32 v78, 16, v199
	v_and_b32_e32 v79, 0xffff0000, v199
	v_lshlrev_b32_e32 v94, 16, v200
	v_and_b32_e32 v95, 0xffff0000, v200
	v_lshlrev_b32_e32 v80, 16, v201
	v_and_b32_e32 v81, 0xffff0000, v201
	v_pk_add_f32 v[62:63], v[62:63], v[72:73]
	v_pk_add_f32 v[60:61], v[60:61], v[70:71]
	v_pk_add_f32 v[58:59], v[58:59], v[76:77]
	v_pk_add_f32 v[56:57], v[56:57], v[74:75]
	v_pk_add_f32 v[70:71], v[42:43], v[84:85]
	v_pk_add_f32 v[72:73], v[40:41], v[98:99]
	v_cvt_pk_bf16_f32 v40, v60, v61
	v_cvt_pk_bf16_f32 v41, v62, v63
	v_cvt_pk_bf16_f32 v42, v56, v57
	v_cvt_pk_bf16_f32 v43, v58, v59
	v_lshlrev_b32_e32 v96, 16, v202
	v_and_b32_e32 v97, 0xffff0000, v202
	v_lshlrev_b32_e32 v82, 16, v203
	v_and_b32_e32 v83, 0xffff0000, v203
	v_pk_add_f32 v[54:55], v[54:55], v[78:79]
	v_pk_add_f32 v[52:53], v[52:53], v[92:93]
	v_pk_add_f32 v[50:51], v[50:51], v[80:81]
	v_pk_add_f32 v[48:49], v[48:49], v[94:95]
	global_store_dwordx4 v[64:65], v[40:43], off
	v_pk_add_f32 v[46:47], v[46:47], v[82:83]
	v_pk_add_f32 v[44:45], v[44:45], v[96:97]
	v_cvt_pk_bf16_f32 v40, v52, v53
	v_cvt_pk_bf16_f32 v41, v54, v55
	v_cvt_pk_bf16_f32 v42, v48, v49
	v_cvt_pk_bf16_f32 v43, v50, v51
	global_store_dwordx4 v[68:69], v[40:43], off
	s_waitcnt vmcnt(14)
	v_lshlrev_b32_e32 v100, 16, v206
	v_and_b32_e32 v101, 0xffff0000, v206
	v_cvt_pk_bf16_f32 v40, v44, v45
	v_cvt_pk_bf16_f32 v41, v46, v47
	v_cvt_pk_bf16_f32 v42, v72, v73
	v_cvt_pk_bf16_f32 v43, v70, v71
	global_store_dwordx4 v[66:67], v[40:43], off
	v_lshlrev_b32_e32 v44, 16, v209
	v_and_b32_e32 v45, 0xffff0000, v209
	v_lshlrev_b32_e32 v40, 16, v207
	v_and_b32_e32 v41, 0xffff0000, v207
	v_lshlrev_b32_e32 v42, 16, v208
	v_and_b32_e32 v43, 0xffff0000, v208
	v_lshl_add_u64 v[48:49], s[12:13], 0, v[90:91]
	v_pk_add_f32 v[38:39], v[38:39], v[40:41]
	v_pk_add_f32 v[36:37], v[36:37], v[100:101]
	v_pk_add_f32 v[40:41], v[34:35], v[44:45]
	v_pk_add_f32 v[34:35], v[32:33], v[42:43]
	v_lshl_add_u64 v[52:53], v[48:49], 0, v[138:139]
	v_cvt_pk_bf16_f32 v32, v36, v37
	v_cvt_pk_bf16_f32 v33, v38, v39
	v_cvt_pk_bf16_f32 v34, v34, v35
	v_cvt_pk_bf16_f32 v35, v40, v41
	s_waitcnt vmcnt(11)
	v_lshlrev_b32_e32 v54, 16, v214
	global_store_dwordx4 v[52:53], v[32:35], off
	s_waitcnt vmcnt(12)
	v_lshlrev_b32_e32 v70, 16, v224
	v_and_b32_e32 v71, 0xffff0000, v224
	v_lshlrev_b32_e32 v32, 16, v210
	v_and_b32_e32 v33, 0xffff0000, v210
	v_lshlrev_b32_e32 v34, 16, v211
	v_and_b32_e32 v35, 0xffff0000, v211
	v_lshlrev_b32_e32 v36, 16, v212
	v_and_b32_e32 v37, 0xffff0000, v212
	v_lshlrev_b32_e32 v38, 16, v213
	v_and_b32_e32 v39, 0xffff0000, v213
	v_lshlrev_b32_e32 v50, 16, v225
	v_and_b32_e32 v51, 0xffff0000, v225
	v_and_b32_e32 v55, 0xffff0000, v214
	v_lshlrev_b32_e32 v40, 16, v215
	v_and_b32_e32 v41, 0xffff0000, v215
	v_lshlrev_b32_e32 v56, 16, v216
	v_and_b32_e32 v57, 0xffff0000, v216
	v_lshlrev_b32_e32 v42, 16, v217
	v_and_b32_e32 v43, 0xffff0000, v217
	v_pk_add_f32 v[30:31], v[30:31], v[34:35]
	v_pk_add_f32 v[28:29], v[28:29], v[32:33]
	v_pk_add_f32 v[26:27], v[26:27], v[38:39]
	v_pk_add_f32 v[24:25], v[24:25], v[36:37]
	v_pk_add_f32 v[32:33], v[2:3], v[50:51]
	v_pk_add_f32 v[34:35], v[0:1], v[70:71]
	v_cvt_pk_bf16_f32 v0, v28, v29
	v_cvt_pk_bf16_f32 v1, v30, v31
	v_cvt_pk_bf16_f32 v2, v24, v25
	v_cvt_pk_bf16_f32 v3, v26, v27
	v_lshlrev_b32_e32 v58, 16, v218
	v_and_b32_e32 v59, 0xffff0000, v218
	v_lshlrev_b32_e32 v44, 16, v219
	v_and_b32_e32 v45, 0xffff0000, v219
	v_lshlrev_b32_e32 v60, 16, v220
	v_and_b32_e32 v61, 0xffff0000, v220
	v_lshlrev_b32_e32 v46, 16, v221
	v_and_b32_e32 v47, 0xffff0000, v221
	v_pk_add_f32 v[22:23], v[22:23], v[40:41]
	v_pk_add_f32 v[20:21], v[20:21], v[54:55]
	v_pk_add_f32 v[18:19], v[18:19], v[42:43]
	v_pk_add_f32 v[16:17], v[16:17], v[56:57]
	global_store_dwordx4 v[64:65], v[0:3], off offset:256
	v_lshlrev_b32_e32 v62, 16, v222
	v_and_b32_e32 v63, 0xffff0000, v222
	v_cvt_pk_bf16_f32 v0, v20, v21
	v_cvt_pk_bf16_f32 v1, v22, v23
	v_cvt_pk_bf16_f32 v2, v16, v17
	v_cvt_pk_bf16_f32 v3, v18, v19
	v_lshlrev_b32_e32 v48, 16, v223
	v_and_b32_e32 v49, 0xffff0000, v223
	v_pk_add_f32 v[14:15], v[14:15], v[44:45]
	v_pk_add_f32 v[12:13], v[12:13], v[58:59]
	v_pk_add_f32 v[10:11], v[10:11], v[46:47]
	v_pk_add_f32 v[8:9], v[8:9], v[60:61]
	global_store_dwordx4 v[68:69], v[0:3], off offset:256
	v_pk_add_f32 v[6:7], v[6:7], v[48:49]
	v_pk_add_f32 v[4:5], v[4:5], v[62:63]
	v_cvt_pk_bf16_f32 v0, v12, v13
	v_cvt_pk_bf16_f32 v1, v14, v15
	v_cvt_pk_bf16_f32 v2, v8, v9
	v_cvt_pk_bf16_f32 v3, v10, v11
	global_store_dwordx4 v[66:67], v[0:3], off offset:256
	s_nop 1
	v_cvt_pk_bf16_f32 v0, v4, v5
	v_cvt_pk_bf16_f32 v1, v6, v7
	v_cvt_pk_bf16_f32 v2, v34, v35
	v_cvt_pk_bf16_f32 v3, v32, v33
	global_store_dwordx4 v[52:53], v[0:3], off offset:256
